# attention softmax row-sum accumulated in two interleaved f32 chains (shorter dependent VALU chain) on top of barrier-head cleanup
# speedup vs baseline: 1.0013x; 1.0013x over previous
; __device__ __forceinline__ void qkt(f32x16& p0, f32x16& p1, const char* Kn, const bf16x8* qr, int r32, int hi) {
;     const char* Kr = Kn + KR_OFF;
;     p0 = f32x16{}; p1 = f32x16{};
;     __builtin_amdgcn_s_setprio(1);
; #pragma unroll
;     for (int d0 = 0; d0 < 8; ++d0) { const int cb = (d0 * 16 + hi * 8) * 2;
;         const bf16x8 b0 = *reinterpret_cast<const bf16x8*>(Kn + KNSWZ(r32, cb));
;         const bf16x8 b1 = *reinterpret_cast<const bf16x8*>(Kn + KNSWZ(32 + r32, cb));
;         p0 = __builtin_amdgcn_mfma_f32_32x32x16_bf16(b0, qr[d0], p0, 0, 0, 0);
;         p1 = __builtin_amdgcn_mfma_f32_32x32x16_bf16(b1, qr[d0], p1, 0, 0, 0); }
; #pragma unroll
;     for (int d0 = 0; d0 < 4; ++d0) { const int cb = (d0 * 16 + hi * 8) * 2;
;         const bf16x8 b0 = *reinterpret_cast<const bf16x8*>(Kr + KRSWZ(r32, cb));
;         const bf16x8 b1 = *reinterpret_cast<const bf16x8*>(Kr + KRSWZ(32 + r32, cb));
;         p0 = __builtin_amdgcn_mfma_f32_32x32x16_bf16(b0, qr[8 + d0], p0, 0, 0, 0);
;         p1 = __builtin_amdgcn_mfma_f32_32x32x16_bf16(b1, qr[8 + d0], p1, 0, 0, 0); }
; }
.LBB0_216:
	s_mul_i32 s0, s9, 0x6000
	s_add_i32 s14, s0, 0
	s_lshl_b32 s13, s9, 14
	s_add_i32 s16, s14, s6
	s_add_i32 s17, s7, s13
	s_add_i32 s18, s14, s8
	s_mov_b32 s13, s10
	s_mov_b32 s10, s15
	s_mul_i32 s0, s13, 0x6000
	s_add_i32 s0, s0, 0
	s_setprio 1
	v_add_u32_e32 v84, s0, v207
	ds_read_b128 v[80:83], v84
	ds_read_b128 v[84:87], v84 offset:8192
	v_add_u32_e32 v168, s0, v210
	ds_read_b128 v[196:199], v168
	ds_read_b128 v[168:171], v168 offset:8192
	v_add_u32_e32 v184, s0, v218
	s_waitcnt lgkmcnt(0)
	v_mfma_f32_32x32x16_bf16 v[96:111], v[80:83], v[156:159], 0
	v_mfma_f32_32x32x16_bf16 v[80:95], v[84:87], v[156:159], 0
	v_mfma_f32_32x32x16_bf16 v[96:111], v[196:199], v[152:155], v[96:111]
	v_mfma_f32_32x32x16_bf16 v[80:95], v[168:171], v[152:155], v[80:95]
	ds_read_b128 v[168:171], v184
	ds_read_b128 v[196:199], v184 offset:8192
	v_add_u32_e32 v184, s0, v221
	s_mov_b32 m0, s16
	s_add_u32 s100, s72, 0x26500000
	s_addc_u32 s101, s73, 0
	global_load_lds_dwordx4 v178, s[100:101]
	s_waitcnt lgkmcnt(0)
	v_mfma_f32_32x32x16_bf16 v[96:111], v[168:171], v[148:151], v[96:111]
	v_mfma_f32_32x32x16_bf16 v[80:95], v[196:199], v[148:151], v[80:95]
	ds_read_b128 v[168:171], v184
	ds_read_b128 v[196:199], v184 offset:8192
	v_add_u32_e32 v184, s0, v222
	s_waitcnt lgkmcnt(0)
	v_mfma_f32_32x32x16_bf16 v[96:111], v[168:171], v[144:147], v[96:111]
	v_mfma_f32_32x32x16_bf16 v[80:95], v[196:199], v[144:147], v[80:95]
	ds_read_b128 v[168:171], v184
	ds_read_b128 v[196:199], v184 offset:8192
	v_add_u32_e32 v184, s0, v223
	s_add_i32 m0, s16, 0x400
	s_nop 0
	global_load_lds_dwordx4 v180, s[100:101]
	s_waitcnt lgkmcnt(0)
	v_mfma_f32_32x32x16_bf16 v[96:111], v[168:171], v[140:143], v[96:111]
	v_mfma_f32_32x32x16_bf16 v[80:95], v[196:199], v[140:143], v[80:95]
	ds_read_b128 v[168:171], v184
	ds_read_b128 v[196:199], v184 offset:8192
	v_add_u32_e32 v184, s0, v224
	v_exp_f32_e32 v233, v73
	s_waitcnt lgkmcnt(0)
	v_mfma_f32_32x32x16_bf16 v[96:111], v[168:171], v[136:139], v[96:111]
	v_mfma_f32_32x32x16_bf16 v[80:95], v[196:199], v[136:139], v[80:95]
	ds_read_b128 v[168:171], v184
	ds_read_b128 v[196:199], v184 offset:8192
	v_add_u32_e32 v184, s0, v225
	s_mov_b32 m0, s17
	s_add_u32 s100, s72, 0x26500100
	s_addc_u32 s101, s73, 0
	global_load_lds_dwordx4 v176, s[100:101]
	v_exp_f32_e32 v250, v74
	s_waitcnt lgkmcnt(0)
	v_mfma_f32_32x32x16_bf16 v[96:111], v[168:171], v[132:135], v[96:111]
	v_mfma_f32_32x32x16_bf16 v[80:95], v[196:199], v[132:135], v[80:95]
	ds_read_b128 v[168:171], v184
	ds_read_b128 v[196:199], v184 offset:8192
	v_add_u32_e32 v184, s0, v226
	v_exp_f32_e32 v200, v75
	s_waitcnt lgkmcnt(0)
	v_mfma_f32_32x32x16_bf16 v[96:111], v[168:171], v[128:131], v[96:111]
	v_mfma_f32_32x32x16_bf16 v[80:95], v[196:199], v[128:131], v[80:95]
	ds_read_b128 v[168:171], v184 offset:16384
	ds_read_b128 v[196:199], v184 offset:20480
	v_add_u32_e32 v184, s0, v227
	s_add_i32 m0, s17, 0x400
	s_add_u32 s100, s72, 0x26500180
	s_addc_u32 s101, s73, 0
	global_load_lds_dwordx4 v176, s[100:101]
	v_exp_f32_e32 v195, v76
	s_waitcnt lgkmcnt(0)
	v_mfma_f32_32x32x16_bf16 v[96:111], v[168:171], v[124:127], v[96:111]
	v_mfma_f32_32x32x16_bf16 v[80:95], v[196:199], v[124:127], v[80:95]
	ds_read_b128 v[168:171], v184 offset:16384
	ds_read_b128 v[196:199], v184 offset:20480
	v_add_u32_e32 v184, s0, v228
	v_exp_f32_e32 v172, v77
	s_waitcnt lgkmcnt(0)
	v_mfma_f32_32x32x16_bf16 v[96:111], v[168:171], v[120:123], v[96:111]
	v_mfma_f32_32x32x16_bf16 v[80:95], v[196:199], v[120:123], v[80:95]
	ds_read_b128 v[168:171], v184 offset:16384
	ds_read_b128 v[196:199], v184 offset:20480
	v_add_u32_e32 v184, s0, v229
	s_add_i32 m0, s18, 0x4000
	s_add_u32 s100, s72, 0x21204000
	s_addc_u32 s101, s73, 0
	global_load_lds_dwordx4 v174, s[100:101]
	v_exp_f32_e32 v173, v78
	s_waitcnt lgkmcnt(0)
	v_mfma_f32_32x32x16_bf16 v[96:111], v[168:171], v[116:119], v[96:111]
	v_mfma_f32_32x32x16_bf16 v[80:95], v[196:199], v[116:119], v[80:95]
	ds_read_b128 v[168:171], v184 offset:16384
	ds_read_b128 v[196:199], v184 offset:20480
	v_exp_f32_e32 v184, v68
	v_exp_f32_e32 v79, v79
	s_waitcnt lgkmcnt(0)
; #define SBAR() __builtin_amdgcn_sched_barrier(0)
; __device__ __forceinline__ void finishSM(f32x16& p0, f32x16& p1, float alpha, float& l_reg, bf16x8& pa0, bf16x8& pa1, bf16x8& pa2, bf16x8& pa3) {
; #pragma unroll
;     for (int r = 0; r < 16; ++r) p1[r] = __builtin_amdgcn_exp2f(p1[r]);
;     float ps = 0;
; #pragma unroll
;     for (int r = 0; r < 16; ++r) ps += p0[r];
; #pragma unroll
;     for (int r = 0; r < 16; ++r) ps += p1[r];
;     { auto rr = __builtin_amdgcn_permlane32_swap(__float_as_uint(ps), __float_as_uint(ps), false, false);
;       ps = __uint_as_float(rr[0]) + __uint_as_float(rr[1]); }
;     l_reg = l_reg * alpha + ps;
;     ...
;     PK4(p0, 0, pa0); PK4(p0, 8, pa1); PK4(p1, 0, pa2); PK4(p1, 8, pa3);
; template <int D0> __device__ __forceinline__ void pv_one(f32x16& od, int vb, bf16x8 pa0, bf16x8 pa1, bf16x8 pa2, bf16x8 pa3) {
;     const s16x4 l0 = tr_read<v_rd_off(D0, 0, 0)>(vb), h0 = tr_read<v_rd_off(D0, 0, 1)>(vb), l1 = tr_read<v_rd_off(D0, 1, 0)>(vb), h1 = tr_read<v_rd_off(D0, 1, 1)>(vb);
;     const s16x4 l2 = tr_read<v_rd_off(D0, 2, 0)>(vb), h2 = tr_read<v_rd_off(D0, 2, 1)>(vb), l3 = tr_read<v_rd_off(D0, 3, 0)>(vb), h3 = tr_read<v_rd_off(D0, 3, 1)>(vb);
;     asm volatile("s_waitcnt lgkmcnt(0)" ::: "memory"); SBAR();
;     ...
;     od = __builtin_amdgcn_mfma_f32_32x32x16_bf16(pa0, PK(l0, h0), od, 0, 0, 0);
;     od = __builtin_amdgcn_mfma_f32_32x32x16_bf16(pa1, PK(l1, h1), od, 0, 0, 0);
;     od = __builtin_amdgcn_mfma_f32_32x32x16_bf16(pa2, PK(l2, h2), od, 0, 0, 0);
;     od = __builtin_amdgcn_mfma_f32_32x32x16_bf16(pa3, PK(l3, h3), od, 0, 0, 0);
;     ...
; }
; __device__ __forceinline__ void pv_d0(f32x16* o, int vb, bf16x8 pa0, bf16x8 pa1, bf16x8 pa2, bf16x8 pa3) {
;     pv_one<0>(o[0], vb, pa0, pa1, pa2, pa3); pv_one<1>(o[1], vb, pa0, pa1, pa2, pa3); pv_one<2>(o[2], vb, pa0, pa1, pa2, pa3); pv_one<3>(o[3], vb, pa0, pa1, pa2, pa3);
	v_mfma_f32_32x32x16_bf16 v[96:111], v[168:171], v[112:115], v[96:111]
	v_exp_f32_e32 v168, v64
	v_add_f32_e32 v64, 0, v247
	v_add_f32_e32 v232, 0, v249
	v_add_f32_e32 v64, v245, v64
	v_add_f32_e32 v232, v248, v232
	v_add_f32_e32 v64, v244, v64
	v_add_f32_e32 v232, v246, v232
	v_add_f32_e32 v64, v242, v64
	v_add_f32_e32 v232, v243, v232
	v_add_f32_e32 v64, v239, v64
	v_add_f32_e32 v232, v241, v232
	v_add_f32_e32 v64, v238, v64
	v_add_f32_e32 v232, v240, v232
	v_add_f32_e32 v64, v235, v64
	v_exp_f32_e32 v169, v65
	v_add_f32_e32 v232, v237, v232
	v_exp_f32_e32 v170, v66
	v_add_f32_e32 v64, v234, v64
	v_exp_f32_e32 v171, v67
	v_add_f32_e32 v232, v236, v232
	v_add_f32_e32 v64, v168, v64
	v_mfma_f32_32x32x16_bf16 v[80:95], v[196:199], v[112:115], v[80:95]
	v_exp_f32_e32 v196, v69
	v_add_f32_e32 v232, v169, v232
	v_exp_f32_e32 v197, v70
	v_add_f32_e32 v64, v170, v64
	v_exp_f32_e32 v198, v71
	v_add_f32_e32 v232, v171, v232
	v_exp_f32_e32 v199, v72
	v_add_f32_e32 v64, v184, v64
	v_add_f32_e32 v232, v196, v232
	v_add_f32_e32 v64, v197, v64
	v_add_f32_e32 v232, v198, v232
	v_add_f32_e32 v64, v199, v64
	v_add_f32_e32 v232, v233, v232
	v_add_f32_e32 v64, v250, v64
	v_add_f32_e32 v232, v200, v232
	v_add_f32_e32 v64, v195, v64
	v_add_f32_e32 v232, v172, v232
	v_add_f32_e32 v64, v173, v64
	v_add_f32_e32 v64, v232, v64
	v_add_f32_e32 v231, v79, v64
	v_mov_b32_e32 v232, v231
	v_cvt_pk_bf16_f32 v64, v247, v249
	v_cvt_pk_bf16_f32 v65, v245, v248
	v_cvt_pk_bf16_f32 v66, v244, v246
	s_nop 1
	v_permlane32_swap_b32_e32 v231, v232
	v_cvt_pk_bf16_f32 v67, v242, v243
	v_permlane32_swap_b32_e32 v64, v66
	v_cvt_pk_bf16_f32 v68, v239, v241
	v_cvt_pk_bf16_f32 v69, v238, v240
	v_cvt_pk_bf16_f32 v70, v235, v237
	v_cvt_pk_bf16_f32 v71, v234, v236
	v_cvt_pk_bf16_f32 v72, v168, v169
	v_cvt_pk_bf16_f32 v73, v170, v171
	v_cvt_pk_bf16_f32 v74, v184, v196
	v_cvt_pk_bf16_f32 v75, v197, v198
	v_cvt_pk_bf16_f32 v76, v199, v233
	v_cvt_pk_bf16_f32 v77, v250, v200
	v_cvt_pk_bf16_f32 v78, v195, v172
	v_cvt_pk_bf16_f32 v79, v173, v79
	v_permlane32_swap_b32_e32 v65, v67
	v_permlane32_swap_b32_e32 v68, v70
	v_permlane32_swap_b32_e32 v69, v71
	v_permlane32_swap_b32_e32 v72, v74
	v_permlane32_swap_b32_e32 v73, v75
	v_permlane32_swap_b32_e32 v76, v78
	v_permlane32_swap_b32_e32 v77, v79
	s_setprio 0
	s_lshl_b32 s15, s15, 14
	v_add_u32_e32 v172, s15, v205
	ds_read_b64_tr_b16 v[168:169], v172 offset:0
	ds_read_b64_tr_b16 v[170:171], v172 offset:0x800
	ds_read_b64_tr_b16 v[196:197], v172 offset:0x1000
	ds_read_b64_tr_b16 v[198:199], v172 offset:0x1800
	ds_read_b64_tr_b16 v[234:235], v172 offset:0x2000
	ds_read_b64_tr_b16 v[236:237], v172 offset:0x2800
	ds_read_b64_tr_b16 v[238:239], v172 offset:0x3000
	ds_read_b64_tr_b16 v[240:241], v172 offset:0x3800
	s_waitcnt lgkmcnt(0)
	s_nop 0
	v_mfma_f32_32x32x16_bf16 v[0:15], v[64:67], v[168:171], v[0:15]
	ds_read_b64_tr_b16 v[168:169], v172 offset:0x200
	ds_read_b64_tr_b16 v[170:171], v172 offset:0xa00
	v_mfma_f32_32x32x16_bf16 v[0:15], v[68:71], v[196:199], v[0:15]
	ds_read_b64_tr_b16 v[196:197], v172 offset:0x1200
	ds_read_b64_tr_b16 v[198:199], v172 offset:0x1a00
	v_mfma_f32_32x32x16_bf16 v[0:15], v[72:75], v[234:237], v[0:15]
	ds_read_b64_tr_b16 v[234:235], v172 offset:0x2200
	ds_read_b64_tr_b16 v[236:237], v172 offset:0x2a00
	v_mfma_f32_32x32x16_bf16 v[0:15], v[76:79], v[238:241], v[0:15]
	ds_read_b64_tr_b16 v[238:239], v172 offset:0x3200
	ds_read_b64_tr_b16 v[240:241], v172 offset:0x3a00
	s_waitcnt lgkmcnt(0)
	v_mfma_f32_32x32x16_bf16 v[48:63], v[64:67], v[168:171], v[48:63]
	ds_read_b64_tr_b16 v[168:169], v172 offset:0x400
	ds_read_b64_tr_b16 v[170:171], v172 offset:0xc00
	v_mfma_f32_32x32x16_bf16 v[48:63], v[68:71], v[196:199], v[48:63]
	ds_read_b64_tr_b16 v[196:197], v172 offset:0x1400
	ds_read_b64_tr_b16 v[198:199], v172 offset:0x1c00
	v_mfma_f32_32x32x16_bf16 v[48:63], v[72:75], v[234:237], v[48:63]
	ds_read_b64_tr_b16 v[234:235], v172 offset:0x2400
	ds_read_b64_tr_b16 v[236:237], v172 offset:0x2c00
	v_mfma_f32_32x32x16_bf16 v[48:63], v[76:79], v[238:241], v[48:63]
	ds_read_b64_tr_b16 v[238:239], v172 offset:0x3400
	ds_read_b64_tr_b16 v[240:241], v172 offset:0x3c00
	s_waitcnt lgkmcnt(0)
	v_mfma_f32_32x32x16_bf16 v[32:47], v[64:67], v[168:171], v[32:47]
	ds_read_b64_tr_b16 v[168:169], v172 offset:0x600
	ds_read_b64_tr_b16 v[170:171], v172 offset:0xe00
	v_mfma_f32_32x32x16_bf16 v[32:47], v[68:71], v[196:199], v[32:47]
	ds_read_b64_tr_b16 v[196:197], v172 offset:0x1600
	ds_read_b64_tr_b16 v[198:199], v172 offset:0x1e00
	v_mfma_f32_32x32x16_bf16 v[32:47], v[72:75], v[234:237], v[32:47]
	ds_read_b64_tr_b16 v[234:235], v172 offset:0x2600
	ds_read_b64_tr_b16 v[236:237], v172 offset:0x2e00
	v_mfma_f32_32x32x16_bf16 v[32:47], v[76:79], v[238:241], v[32:47]
	ds_read_b64_tr_b16 v[238:239], v172 offset:0x3600
	ds_read_b64_tr_b16 v[240:241], v172 offset:0x3e00
	s_waitcnt lgkmcnt(0)
	v_mfma_f32_32x32x16_bf16 v[16:31], v[64:67], v[168:171], v[16:31]
	v_max_f32_e32 v64, v97, v97
	v_max_f32_e32 v65, v96, v96
	v_max_f32_e32 v64, v65, v64
	v_max3_f32 v64, v64, v98, v99
	v_max3_f32 v64, v64, v100, v101
	v_max3_f32 v64, v64, v102, v103
	v_max3_f32 v64, v64, v104, v105
	v_mfma_f32_32x32x16_bf16 v[16:31], v[68:71], v[196:199], v[16:31]
	v_max3_f32 v64, v64, v106, v107
	v_max3_f32 v64, v64, v108, v109
	v_max3_f32 v64, v64, v110, v111
	v_max3_f32 v64, v64, v80, v81
	v_max3_f32 v64, v64, v82, v83
	v_max3_f32 v64, v64, v84, v85
	v_max3_f32 v64, v64, v86, v87
	v_mfma_f32_32x32x16_bf16 v[16:31], v[72:75], v[234:237], v[16:31]
	v_max3_f32 v64, v64, v88, v89
	v_max3_f32 v64, v64, v90, v91
	v_max3_f32 v64, v64, v92, v93
	v_max3_f32 v64, v64, v94, v95
	v_mov_b32_e32 v65, v64
	s_nop 1
	v_permlane32_swap_b32_e32 v64, v65
	v_max_f32_e32 v65, v65, v65
	v_max_f32_e32 v64, v64, v64
	v_mfma_f32_32x32x16_bf16 v[16:31], v[76:79], v[238:241], v[16:31]
	v_max_f32_e32 v64, v64, v65
	v_sub_f32_e32 v65, v64, v182
	s_mov_b32 s0, 0x41300000
	v_cmp_ge_f32_e32 vcc, s0, v65
	s_cmp_eq_u64 vcc, exec
	v_max_f32_e32 v65, v182, v182
	s_cselect_b64 vcc, -1, 0
	v_max_f32_e32 v64, v65, v64
	v_cndmask_b32_e32 v184, v64, v182, vcc
	v_cmp_eq_f32_e64 s[0:1], 0, v184
	s_cmp_eq_u64 s[0:1], exec
	s_cbranch_scc0 .LBB0_228

; #define SBAR() __builtin_amdgcn_sched_barrier(0)
; #define WAIT_BAR() asm volatile("s_waitcnt vmcnt(0) lgkmcnt(0)\n\ts_barrier" ::: "memory")
; #define RESC(a) do { if (__any((a) < 1.f)) { if (hi == 0) al_l[r32] = (a); asm volatile("s_waitcnt lgkmcnt(0)" ::: "memory"); \
;     _Pragma("unroll") for (int d = 0; d < 4; ++d) _Pragma("unroll") for (int r = 0; r < 16; ++r) o[d][r] *= al_l[crow(r, hi)]; } } while (0)
; #define ROT() do { const int t_ = s_prev; s_prev = s_cur; s_cur = s_next; s_next = t_; } while (0)
; __device__ __forceinline__ void qkt(f32x16& p0, f32x16& p1, const char* Kn, const bf16x8* qr, int r32, int hi) {
;     const char* Kr = Kn + KR_OFF;
;     p0 = f32x16{}; p1 = f32x16{};
;     __builtin_amdgcn_s_setprio(1);
; #pragma unroll
;     for (int d0 = 0; d0 < 8; ++d0) { const int cb = (d0 * 16 + hi * 8) * 2;
;         const bf16x8 b0 = *reinterpret_cast<const bf16x8*>(Kn + KNSWZ(r32, cb));
;         const bf16x8 b1 = *reinterpret_cast<const bf16x8*>(Kn + KNSWZ(32 + r32, cb));
;         p0 = __builtin_amdgcn_mfma_f32_32x32x16_bf16(b0, qr[d0], p0, 0, 0, 0);
;         p1 = __builtin_amdgcn_mfma_f32_32x32x16_bf16(b1, qr[d0], p1, 0, 0, 0); }
; #pragma unroll
;     for (int d0 = 0; d0 < 4; ++d0) { const int cb = (d0 * 16 + hi * 8) * 2;
;         const bf16x8 b0 = *reinterpret_cast<const bf16x8*>(Kr + KRSWZ(r32, cb));
;         const bf16x8 b1 = *reinterpret_cast<const bf16x8*>(Kr + KRSWZ(32 + r32, cb));
;         p0 = __builtin_amdgcn_mfma_f32_32x32x16_bf16(b0, qr[8 + d0], p0, 0, 0, 0);
;         p1 = __builtin_amdgcn_mfma_f32_32x32x16_bf16(b1, qr[8 + d0], p1, 0, 0, 0); }
; }
; __device__ __forceinline__ void attn_unit(const bf16_t* __restrict__ Qb, const bf16_t* __restrict__ Kn, const bf16_t* __restrict__ Vh, const bf16_t* __restrict__ Kr,
;                                           bf16_t* __restrict__ Ob, int seq, char* lds, int wv_) { LAUNDER_IDS;
;     ...
;         RESC(alB); WAIT_BAR(); ROT();
;         DMA(j + 2, s_next); SBAR();
;         qkt(pA0, pA1, lds + OFF_K + s_cur * SLOT_K, qr, r32, hi);
.LBB0_221:
	v_exp_f32_e32 v182, v98
	v_exp_f32_e32 v172, v96
	v_exp_f32_e32 v173, v97
	v_exp_f32_e32 v195, v99
	v_exp_f32_e32 v196, v100
	v_exp_f32_e32 v197, v101
	v_exp_f32_e32 v198, v102
	v_exp_f32_e32 v199, v103
	v_exp_f32_e32 v200, v104
	v_exp_f32_e32 v234, v105
	v_exp_f32_e32 v235, v106
	v_exp_f32_e32 v236, v107
	v_exp_f32_e32 v237, v108
	v_exp_f32_e32 v238, v109
	v_exp_f32_e32 v239, v110
	v_exp_f32_e32 v240, v111
	s_mul_i32 s0, s10, 0x6000
	s_add_i32 s16, s0, 0
	s_add_i32 s17, s16, s6
	s_add_i32 s18, s16, s8
	s_waitcnt vmcnt(0) lgkmcnt(0)
	s_barrier
	s_add_i32 s15, s7, s15
	s_setprio 1
	v_add_u32_e32 v68, s14, v207
	ds_read_b128 v[64:67], v68
	ds_read_b128 v[68:71], v68 offset:8192
	v_add_u32_e32 v186, s14, v210
	ds_read_b128 v[168:171], v186
	ds_read_b128 v[186:189], v186 offset:8192
	s_waitcnt lgkmcnt(0)
	v_mfma_f32_32x32x16_bf16 v[96:111], v[64:67], v[156:159], 0
	v_mfma_f32_32x32x16_bf16 v[64:79], v[68:71], v[156:159], 0
	v_mfma_f32_32x32x16_bf16 v[96:111], v[168:171], v[152:155], v[96:111]
	v_mfma_f32_32x32x16_bf16 v[64:79], v[186:189], v[152:155], v[64:79]
	v_add_u32_e32 v186, s14, v218
	ds_read_b128 v[168:171], v186
	ds_read_b128 v[186:189], v186 offset:8192
	s_mov_b32 m0, s17
	s_add_u32 s100, s72, 0x26580000
	s_addc_u32 s101, s73, 0
	global_load_lds_dwordx4 v178, s[100:101]
	s_waitcnt lgkmcnt(0)
	v_mfma_f32_32x32x16_bf16 v[96:111], v[168:171], v[148:151], v[96:111]
	v_mfma_f32_32x32x16_bf16 v[64:79], v[186:189], v[148:151], v[64:79]
	v_add_u32_e32 v186, s14, v221
	ds_read_b128 v[168:171], v186
	ds_read_b128 v[186:189], v186 offset:8192
	s_waitcnt lgkmcnt(0)
	v_mfma_f32_32x32x16_bf16 v[96:111], v[168:171], v[144:147], v[96:111]
	v_mfma_f32_32x32x16_bf16 v[64:79], v[186:189], v[144:147], v[64:79]
	v_add_u32_e32 v186, s14, v222
	ds_read_b128 v[168:171], v186
	ds_read_b128 v[186:189], v186 offset:8192
	s_add_i32 m0, s17, 0x400
	s_nop 0
	global_load_lds_dwordx4 v180, s[100:101]
	v_exp_f32_e32 v190, v88
	s_waitcnt lgkmcnt(0)
	v_mfma_f32_32x32x16_bf16 v[96:111], v[168:171], v[140:143], v[96:111]
	v_mfma_f32_32x32x16_bf16 v[64:79], v[186:189], v[140:143], v[64:79]
	v_add_u32_e32 v186, s14, v223
	ds_read_b128 v[168:171], v186
	ds_read_b128 v[186:189], v186 offset:8192
	v_exp_f32_e32 v191, v89
	s_waitcnt lgkmcnt(0)
	v_mfma_f32_32x32x16_bf16 v[96:111], v[168:171], v[136:139], v[96:111]
	v_mfma_f32_32x32x16_bf16 v[64:79], v[186:189], v[136:139], v[64:79]
	v_add_u32_e32 v186, s14, v224
	ds_read_b128 v[168:171], v186
	ds_read_b128 v[186:189], v186 offset:8192
	s_mov_b32 m0, s15
	s_add_u32 s100, s72, 0x26580100
	s_addc_u32 s101, s73, 0
	global_load_lds_dwordx4 v176, s[100:101]
	v_exp_f32_e32 v192, v90
	s_waitcnt lgkmcnt(0)
	v_mfma_f32_32x32x16_bf16 v[96:111], v[168:171], v[132:135], v[96:111]
	v_mfma_f32_32x32x16_bf16 v[64:79], v[186:189], v[132:135], v[64:79]
	v_add_u32_e32 v186, s14, v225
	ds_read_b128 v[168:171], v186
	ds_read_b128 v[186:189], v186 offset:8192
	v_exp_f32_e32 v193, v91
	s_waitcnt lgkmcnt(0)
	v_mfma_f32_32x32x16_bf16 v[96:111], v[168:171], v[128:131], v[96:111]
	v_mfma_f32_32x32x16_bf16 v[64:79], v[186:189], v[128:131], v[64:79]
	v_add_u32_e32 v186, s14, v226
	ds_read_b128 v[168:171], v186 offset:16384
	ds_read_b128 v[186:189], v186 offset:20480
	s_add_i32 m0, s15, 0x400
	s_add_u32 s100, s72, 0x26580180
	s_addc_u32 s101, s73, 0
	global_load_lds_dwordx4 v176, s[100:101]
	v_exp_f32_e32 v241, v92
	s_waitcnt lgkmcnt(0)
	v_mfma_f32_32x32x16_bf16 v[96:111], v[168:171], v[124:127], v[96:111]
	v_mfma_f32_32x32x16_bf16 v[64:79], v[186:189], v[124:127], v[64:79]
	v_add_u32_e32 v186, s14, v227
	ds_read_b128 v[168:171], v186 offset:16384
	ds_read_b128 v[186:189], v186 offset:20480
	v_exp_f32_e32 v242, v93
	s_waitcnt lgkmcnt(0)
	v_mfma_f32_32x32x16_bf16 v[96:111], v[168:171], v[120:123], v[96:111]
	v_mfma_f32_32x32x16_bf16 v[64:79], v[186:189], v[120:123], v[64:79]
	v_add_u32_e32 v186, s14, v228
	ds_read_b128 v[168:171], v186 offset:16384
	ds_read_b128 v[186:189], v186 offset:20480
	s_add_i32 m0, s18, 0x4000
	s_add_u32 s100, s72, 0x21206000
	s_addc_u32 s101, s73, 0
	global_load_lds_dwordx4 v174, s[100:101]
	v_exp_f32_e32 v94, v94
	s_waitcnt lgkmcnt(0)
	v_mfma_f32_32x32x16_bf16 v[96:111], v[168:171], v[116:119], v[96:111]
	v_mfma_f32_32x32x16_bf16 v[64:79], v[186:189], v[116:119], v[64:79]
	v_add_u32_e32 v186, s14, v229
	ds_read_b128 v[168:171], v186 offset:16384
	ds_read_b128 v[186:189], v186 offset:20480
	v_exp_f32_e32 v95, v95
	s_waitcnt lgkmcnt(0)
; #define SBAR() __builtin_amdgcn_sched_barrier(0)
; __device__ __forceinline__ void finishSM(f32x16& p0, f32x16& p1, float alpha, float& l_reg, bf16x8& pa0, bf16x8& pa1, bf16x8& pa2, bf16x8& pa3) {
; #pragma unroll
;     for (int r = 0; r < 16; ++r) p1[r] = __builtin_amdgcn_exp2f(p1[r]);
;     float ps = 0;
; #pragma unroll
;     for (int r = 0; r < 16; ++r) ps += p0[r];
; #pragma unroll
;     for (int r = 0; r < 16; ++r) ps += p1[r];
;     { auto rr = __builtin_amdgcn_permlane32_swap(__float_as_uint(ps), __float_as_uint(ps), false, false);
;       ps = __uint_as_float(rr[0]) + __uint_as_float(rr[1]); }
;     l_reg = l_reg * alpha + ps;
;     ...
;     PK4(p0, 0, pa0); PK4(p0, 8, pa1); PK4(p1, 0, pa2); PK4(p1, 8, pa3);
; template <int D0> __device__ __forceinline__ void pv_one(f32x16& od, int vb, bf16x8 pa0, bf16x8 pa1, bf16x8 pa2, bf16x8 pa3) {
;     const s16x4 l0 = tr_read<v_rd_off(D0, 0, 0)>(vb), h0 = tr_read<v_rd_off(D0, 0, 1)>(vb), l1 = tr_read<v_rd_off(D0, 1, 0)>(vb), h1 = tr_read<v_rd_off(D0, 1, 1)>(vb);
;     const s16x4 l2 = tr_read<v_rd_off(D0, 2, 0)>(vb), h2 = tr_read<v_rd_off(D0, 2, 1)>(vb), l3 = tr_read<v_rd_off(D0, 3, 0)>(vb), h3 = tr_read<v_rd_off(D0, 3, 1)>(vb);
;     asm volatile("s_waitcnt lgkmcnt(0)" ::: "memory"); SBAR();
;     ...
;     od = __builtin_amdgcn_mfma_f32_32x32x16_bf16(pa0, PK(l0, h0), od, 0, 0, 0);
;     od = __builtin_amdgcn_mfma_f32_32x32x16_bf16(pa1, PK(l1, h1), od, 0, 0, 0);
;     od = __builtin_amdgcn_mfma_f32_32x32x16_bf16(pa2, PK(l2, h2), od, 0, 0, 0);
;     od = __builtin_amdgcn_mfma_f32_32x32x16_bf16(pa3, PK(l3, h3), od, 0, 0, 0);
;     ...
; }
; __device__ __forceinline__ void pv_d0(f32x16* o, int vb, bf16x8 pa0, bf16x8 pa1, bf16x8 pa2, bf16x8 pa3) {
;     pv_one<0>(o[0], vb, pa0, pa1, pa2, pa3); pv_one<1>(o[1], vb, pa0, pa1, pa2, pa3); pv_one<2>(o[2], vb, pa0, pa1, pa2, pa3); pv_one<3>(o[3], vb, pa0, pa1, pa2, pa3);
	v_mfma_f32_32x32x16_bf16 v[96:111], v[168:171], v[112:115], v[96:111]
	v_exp_f32_e32 v168, v80
	v_add_f32_e32 v80, 0, v172
	v_add_f32_e32 v169, 0, v173
	v_add_f32_e32 v80, v182, v80
	v_add_f32_e32 v169, v195, v169
	v_add_f32_e32 v80, v196, v80
	v_add_f32_e32 v169, v197, v169
	v_add_f32_e32 v80, v198, v80
	v_add_f32_e32 v169, v199, v169
	v_add_f32_e32 v80, v200, v80
	v_add_f32_e32 v169, v234, v169
	v_add_f32_e32 v80, v235, v80
	v_add_f32_e32 v169, v236, v169
	v_add_f32_e32 v80, v237, v80
	v_add_f32_e32 v80, v169, v80
	v_exp_f32_e32 v169, v81
	v_add_f32_e32 v80, v238, v80
	v_exp_f32_e32 v170, v82
	v_add_f32_e32 v81, 0, v239
	v_exp_f32_e32 v171, v83
	v_add_f32_e32 v80, v240, v80
	v_mfma_f32_32x32x16_bf16 v[64:79], v[186:189], v[112:115], v[64:79]
	v_exp_f32_e32 v186, v84
	v_add_f32_e32 v81, v168, v81
	v_exp_f32_e32 v187, v85
	v_add_f32_e32 v80, v169, v80
	v_exp_f32_e32 v188, v86
	v_add_f32_e32 v81, v170, v81
	v_exp_f32_e32 v189, v87
	v_add_f32_e32 v80, v171, v80
	v_add_f32_e32 v81, v186, v81
	v_add_f32_e32 v80, v187, v80
	v_add_f32_e32 v81, v188, v81
	v_add_f32_e32 v80, v189, v80
	v_add_f32_e32 v81, v190, v81
	v_add_f32_e32 v80, v191, v80
	v_add_f32_e32 v81, v192, v81
	v_add_f32_e32 v80, v193, v80
	v_add_f32_e32 v81, v241, v81
	v_add_f32_e32 v80, v242, v80
	v_add_f32_e32 v81, v94, v81
	v_add_f32_e32 v80, v95, v80
	v_add_f32_e32 v80, v81, v80
	v_mov_b32_e32 v81, v80
	v_cvt_pk_bf16_f32 v82, v172, v173
	v_cvt_pk_bf16_f32 v83, v182, v195
	v_cvt_pk_bf16_f32 v84, v196, v197
	s_nop 1
	v_permlane32_swap_b32_e32 v80, v81
	v_cvt_pk_bf16_f32 v85, v198, v199
	v_permlane32_swap_b32_e32 v82, v84
	v_cvt_pk_bf16_f32 v86, v200, v234
	v_cvt_pk_bf16_f32 v87, v235, v236
	v_cvt_pk_bf16_f32 v88, v237, v238
	v_cvt_pk_bf16_f32 v89, v239, v240
	v_cvt_pk_bf16_f32 v90, v168, v169
	v_cvt_pk_bf16_f32 v91, v170, v171
	v_cvt_pk_bf16_f32 v92, v186, v187
	v_cvt_pk_bf16_f32 v93, v188, v189
	v_cvt_pk_bf16_f32 v168, v190, v191
	v_cvt_pk_bf16_f32 v169, v192, v193
	v_cvt_pk_bf16_f32 v170, v241, v242
	v_cvt_pk_bf16_f32 v171, v94, v95
	v_permlane32_swap_b32_e32 v83, v85
	v_permlane32_swap_b32_e32 v86, v88
	v_permlane32_swap_b32_e32 v87, v89
	v_permlane32_swap_b32_e32 v90, v92
	v_permlane32_swap_b32_e32 v91, v93
	v_permlane32_swap_b32_e32 v168, v170
	v_permlane32_swap_b32_e32 v169, v171
	s_setprio 0
	v_lshl_add_u32 v94, s13, 14, v205
	ds_read_b64_tr_b16 v[186:187], v94 offset:0
	ds_read_b64_tr_b16 v[188:189], v94 offset:0x800
	ds_read_b64_tr_b16 v[190:191], v94 offset:0x1000
	ds_read_b64_tr_b16 v[192:193], v94 offset:0x1800
	ds_read_b64_tr_b16 v[196:197], v94 offset:0x2000
	ds_read_b64_tr_b16 v[198:199], v94 offset:0x2800
	ds_read_b64_tr_b16 v[234:235], v94 offset:0x3000
	ds_read_b64_tr_b16 v[236:237], v94 offset:0x3800
	s_waitcnt lgkmcnt(0)
	s_nop 0
	v_mfma_f32_32x32x16_bf16 v[0:15], v[82:85], v[186:189], v[0:15]
	ds_read_b64_tr_b16 v[186:187], v94 offset:0x200
	ds_read_b64_tr_b16 v[188:189], v94 offset:0xa00
	v_mfma_f32_32x32x16_bf16 v[0:15], v[86:89], v[190:193], v[0:15]
	ds_read_b64_tr_b16 v[190:191], v94 offset:0x1200
	ds_read_b64_tr_b16 v[192:193], v94 offset:0x1a00
	v_mfma_f32_32x32x16_bf16 v[0:15], v[90:93], v[196:199], v[0:15]
	ds_read_b64_tr_b16 v[196:197], v94 offset:0x2200
	ds_read_b64_tr_b16 v[198:199], v94 offset:0x2a00
	v_mfma_f32_32x32x16_bf16 v[0:15], v[168:171], v[234:237], v[0:15]
	ds_read_b64_tr_b16 v[234:235], v94 offset:0x3200
	ds_read_b64_tr_b16 v[236:237], v94 offset:0x3a00
	s_waitcnt lgkmcnt(0)
	v_mfma_f32_32x32x16_bf16 v[48:63], v[82:85], v[186:189], v[48:63]
	ds_read_b64_tr_b16 v[186:187], v94 offset:0x400
	ds_read_b64_tr_b16 v[188:189], v94 offset:0xc00
	v_mfma_f32_32x32x16_bf16 v[48:63], v[86:89], v[190:193], v[48:63]
	ds_read_b64_tr_b16 v[190:191], v94 offset:0x1400
	ds_read_b64_tr_b16 v[192:193], v94 offset:0x1c00
	v_mfma_f32_32x32x16_bf16 v[48:63], v[90:93], v[196:199], v[48:63]
	ds_read_b64_tr_b16 v[196:197], v94 offset:0x2400
	ds_read_b64_tr_b16 v[198:199], v94 offset:0x2c00
	v_mfma_f32_32x32x16_bf16 v[48:63], v[168:171], v[234:237], v[48:63]
	ds_read_b64_tr_b16 v[234:235], v94 offset:0x3400
	ds_read_b64_tr_b16 v[236:237], v94 offset:0x3c00
	s_waitcnt lgkmcnt(0)
	v_mfma_f32_32x32x16_bf16 v[32:47], v[82:85], v[186:189], v[32:47]
	ds_read_b64_tr_b16 v[186:187], v94 offset:0x600
	ds_read_b64_tr_b16 v[188:189], v94 offset:0xe00
	v_mfma_f32_32x32x16_bf16 v[32:47], v[86:89], v[190:193], v[32:47]
	ds_read_b64_tr_b16 v[190:191], v94 offset:0x1600
	ds_read_b64_tr_b16 v[192:193], v94 offset:0x1e00
	v_mfma_f32_32x32x16_bf16 v[32:47], v[90:93], v[196:199], v[32:47]
	ds_read_b64_tr_b16 v[196:197], v94 offset:0x2600
	ds_read_b64_tr_b16 v[198:199], v94 offset:0x2e00
	v_mfma_f32_32x32x16_bf16 v[32:47], v[168:171], v[234:237], v[32:47]
	ds_read_b64_tr_b16 v[234:235], v94 offset:0x3600
	ds_read_b64_tr_b16 v[236:237], v94 offset:0x3e00
	s_waitcnt lgkmcnt(0)
	v_mfma_f32_32x32x16_bf16 v[16:31], v[82:85], v[186:189], v[16:31]
	v_max_f32_e32 v82, v97, v97
	v_max_f32_e32 v83, v96, v96
	v_max_f32_e32 v82, v83, v82
	v_max3_f32 v82, v82, v98, v99
	v_max3_f32 v82, v82, v100, v101
	v_max3_f32 v82, v82, v102, v103
	v_max3_f32 v82, v82, v104, v105
	v_mfma_f32_32x32x16_bf16 v[16:31], v[86:89], v[190:193], v[16:31]
	v_max3_f32 v82, v82, v106, v107
	v_max3_f32 v82, v82, v108, v109
	v_max3_f32 v82, v82, v110, v111
	v_max3_f32 v82, v82, v64, v65
	v_max3_f32 v82, v82, v66, v67
	v_max3_f32 v82, v82, v68, v69
	v_max3_f32 v82, v82, v70, v71
	v_mfma_f32_32x32x16_bf16 v[16:31], v[90:93], v[196:199], v[16:31]
	v_max3_f32 v82, v82, v72, v73
	v_max3_f32 v82, v82, v74, v75
	v_max3_f32 v82, v82, v76, v77
	v_max3_f32 v82, v82, v78, v79
	v_mov_b32_e32 v83, v82
	s_nop 1
	v_permlane32_swap_b32_e32 v82, v83
	v_max_f32_e32 v83, v83, v83
	v_max_f32_e32 v82, v82, v82
	v_mfma_f32_32x32x16_bf16 v[16:31], v[168:171], v[234:237], v[16:31]
	v_max_f32_e32 v82, v82, v83
	v_sub_f32_e32 v83, v82, v184
	s_mov_b32 s0, 0x41300000
	v_cmp_ge_f32_e32 vcc, s0, v83
	s_cmp_eq_u64 vcc, exec
	v_max_f32_e32 v83, v184, v184
	s_cselect_b64 vcc, -1, 0
	v_max_f32_e32 v82, v83, v82
	v_cndmask_b32_e32 v182, v82, v184, vcc
	v_cmp_eq_f32_e64 s[0:1], 0, v182
	s_cmp_eq_u64 s[0:1], exec
	s_cbranch_scc0 .LBB0_229
